# grid barrier after the last layer's residual phase removed (nothing follows it before the kernel ends)
# speedup vs baseline: 1.0034x; 1.0034x over previous
.LBB0_964:
	v_readlane_b32 s0, v229, 47
	s_cmp_eq_u32 s0, 3
	s_cbranch_scc1 .LBB0_1015
	s_waitcnt vmcnt(0)
	s_waitcnt lgkmcnt(0)
	s_barrier
	s_mov_b64 s[0:1], exec
	v_readlane_b32 s4, v230, 15
	v_readlane_b32 s5, v230, 16
	s_and_b64 s[4:5], s[0:1], s[4:5]
	s_mov_b64 exec, s[4:5]
	s_cbranch_execz .LBB0_138
	v_readlane_b32 s2, v230, 17
	s_waitcnt vmcnt(0) expcnt(0) lgkmcnt(0)
	ds_read_b32 v3, v195
	ds_read_b32 v2, v196
	s_waitcnt lgkmcnt(1)
	v_cmp_ne_u32_e32 vcc, 0, v3
	s_cbranch_vccnz .LBB0_980
	s_mov_b32 s8, 1
	s_branch .LBB0_968
